# dilated item: workgroup-consecutive order only when the grid is 256 workgroups, plain order otherwise
# baseline (speedup 1.0000x reference)
; DI int otid() { int t = threadIdx.x; asm volatile("" : "+v"(t)); return t; }
; DI void swin_attn_item(KP p, int item, u16* sm) {
;   const int tid = otid(), lane = tid & 63, w = __builtin_amdgcn_readfirstlane(tid >> 6), r = lane & 31, hh = lane >> 5;
;   u16* Ks = sm; u16* Vs = sm + 4 * KS_BUF;
;   const int bhp = item >> 6, sub = item & 63;
;   const int pat = bhp % 3, bh = bhp / 3, head = bh % 6, b = bh / 6;
;   const int sh = 2 * pat, L = S >> sh;
;   const int cls = sub >> (6 - sh), pb = sub & ((64 >> sh) - 1);
;   const int P = pb * 256;
;   const int qp = P + 32 * w + r, tq = cls + (qp << sh);
;   const u16* prow = p.proj + (size_t)b * S * NPROJ;
;   bf16x8 qf[4];
; #pragma unroll
;   for (int s = 0; s < 4; ++s) qf[s] = *(const bf16x8*)(prow + (size_t)tq * NPROJ + 768 + head * 64 + s * 16 + 8 * hh);
;   f32x16 O[2];
; #pragma unroll
;   for (int mb = 0; mb < 2; ++mb)
; #pragma unroll
;     for (int i = 0; i < 16; ++i) O[mb][i] = 0.f;
;   float m_run = -1e20f, l_run = 0.f;
;   const int key0 = tid >> 3, ch = tid & 7;
;   const u16* kg = prow + 1152 + head * 64 + ch * 8;
;   auto gk = [&](int j) __attribute__((always_inline)) -> const u16* {
;     int kp = P - 64 + 64 * j + key0; kp = kp < 0 ? 0 : (kp > L - 1 ? L - 1 : kp);
;     return kg + (size_t)(cls + (kp << sh)) * NPROJ;
;   };
;   const uint4 k0 = *(const uint4*)gk(0), v0 = *(const uint4*)(gk(0) + 384), k1 = *(const uint4*)gk(1), v1 = *(const uint4*)(gk(1) + 384);
;   const uint4 k2 = *(const uint4*)gk(2), v2 = *(const uint4*)(gk(2) + 384), k3 = *(const uint4*)gk(3), v3 = *(const uint4*)(gk(3) + 384);
; DI void phase_local(KP p, int layer, u16* sm) {
;     ...
;     if (it < N_DIL) swin_attn_item(p, (it & 7) * (N_DIL / 8) + (it >> 3), sm);
.LBB0_325:
	s_mov_b32 s6, s23
	s_mov_b32 s101, 0
	s_cmpk_lg_u32 s74, 0x100
	s_cbranch_scc1 .Ldil_item_known
	s_mul_i32 s6, s2, 9
	s_lshr_b32 s101, s23, 8
	s_add_i32 s6, s6, s101
.Ldil_item_known:
	s_lshr_b32 s7, s6, 6
	s_and_b32 s36, s6, 63
	s_mul_i32 s37, s7, 43
	s_lshr_b32 s37, s37, 7
	s_mul_i32 s38, s37, 3
	s_sub_i32 s38, s7, s38
	s_cmp_ge_u32 s37, 6
	s_cselect_b32 s39, 1, 0
	s_mul_i32 s40, s39, 6
	s_sub_i32 s40, s37, s40
	s_lshl_b32 s41, s38, 1
	s_lshr_b32 s42, 0x4000, s41
	s_sub_i32 s43, 6, s41
	s_lshr_b32 s44, s36, s43
	s_lshr_b32 s45, 64, s41
	s_add_i32 s45, s45, -1
	s_and_b32 s45, s36, s45
	s_lshl_b32 s46, s45, 8
	s_min_u32 s100, s101, s45
	s_min_u32 s100, s100, 1
	v_readfirstlane_b32 s47, v224
	v_and_b32_e32 v2, 31, v224
	v_bfe_u32 v3, v224, 5, 1
	v_lshrrev_b32_e32 v12, 3, v224
	v_and_b32_e32 v13, 7, v224
	s_lshr_b32 s47, s47, 6
	s_cmp_eq_u32 s39, 0
	s_cselect_b32 s12, 0, 0x6000000
	s_add_u32 s16, s78, s12
	s_addc_u32 s17, s79, 0
	s_lshl_b32 s12, s40, 7
	s_add_u32 s16, s16, s12
	s_addc_u32 s17, s17, 0
	s_lshl_b32 s12, s47, 5
	s_add_i32 s12, s12, s46
	v_add_u32_e32 v15, s12, v2
	v_lshlrev_b32_e32 v15, s41, v15
	v_add_u32_e32 v15, s44, v15
	v_lshlrev_b32_e32 v0, 4, v3
	v_mov_b32_e32 v186, s16
	v_mov_b32_e32 v187, s17
	v_lshl_add_u64 v[188:189], v[186:187], 0, v[0:1]
	v_mad_u64_u32 v[184:185], s[18:19], v15, s9, v[188:189]
	global_load_dwordx4 v[96:99], v[184:185], off offset:1536
	global_load_dwordx4 v[100:103], v[184:185], off offset:1568
	global_load_dwordx4 v[104:107], v[184:185], off offset:1600
	global_load_dwordx4 v[108:111], v[184:185], off offset:1632
	v_lshlrev_b32_e32 v0, 4, v13
	v_lshl_add_u64 v[10:11], v[186:187], 0, v[0:1]
	s_add_i32 s12, s46, 0xffffffc0
	v_add_u32_e32 v14, s12, v12
	s_add_i32 s18, s42, -1
	s_cmp_eq_u32 s100, 1
	s_cbranch_scc1 .Ldil_have_t01
	v_mov_b32_e32 v0, v14
	v_max_i32_e32 v0, 0, v0
	v_min_i32_e32 v0, s18, v0
	v_lshlrev_b32_e32 v0, s41, v0
	v_add_u32_e32 v0, s44, v0
	v_mad_u64_u32 v[184:185], s[20:21], v0, s9, v[10:11]
	global_load_dwordx4 v[136:139], v[184:185], off offset:2304
	global_load_dwordx4 v[140:143], v[184:185], off offset:3072
	v_add_u32_e32 v0, 64, v14
	v_max_i32_e32 v0, 0, v0
	v_min_i32_e32 v0, s18, v0
	v_lshlrev_b32_e32 v0, s41, v0
	v_add_u32_e32 v0, s44, v0
	v_mad_u64_u32 v[184:185], s[20:21], v0, s9, v[10:11]
	global_load_dwordx4 v[144:147], v[184:185], off offset:2304
	global_load_dwordx4 v[148:151], v[184:185], off offset:3072
